# hand-written rms_norm loops: 32 contiguous rows per wave, sc/sh/g kept in registers, 4 rows of loads in flight (on top of flat->global)
# speedup vs baseline: 1.0164x; 1.0164x over previous
.LBB0_8:
	s_mov_b32 s15, s2
	s_mov_b64 s[6:7], -1
	s_mov_b64 s[0:1], 0
	s_cmp_lt_i32 s2, 19
	s_mov_b64 s[4:5], 0
	s_cbranch_scc1 .LBB0_17
	s_cmp_eq_u32 s15, 19
	s_mov_b64 s[4:5], -1
	s_cbranch_scc0 .LBB0_16
	v_mov_b32_e32 v0, 0xe0
	v_mov_b32_e32 v2, 0xd8
	v_add_u32_e32 v0, s91, v0
	ds_read_b64 v[0:1], v0
	v_mov_b32_e32 v4, 0xe0
	v_add_u32_e32 v2, s91, v2
	ds_read_b64 v[2:3], v2
	s_waitcnt lgkmcnt(0)
	v_readfirstlane_b32 s9, v1
	v_add_u32_e32 v4, s91, v4
	ds_read_b64 v[4:5], v4
	v_readfirstlane_b32 s8, v0
	v_mbcnt_lo_u32_b32 v0, -1, 0
	v_mbcnt_hi_u32_b32 v0, -1, v0
	v_readlane_b32 s2, v253, 11
	v_add_u32_e32 v1, s57, v0
	v_ashrrev_i32_e32 v1, 6, v1
	v_add_u32_e32 v52, s2, v1
	s_waitcnt lgkmcnt(1)
	v_readfirstlane_b32 s11, v3
	v_readfirstlane_b32 s10, v2
	s_waitcnt lgkmcnt(0)
	v_readfirstlane_b32 s7, v5
	v_readfirstlane_b32 s6, v4
	v_cmp_gt_i32_e32 vcc, s3, v52
	s_and_saveexec_b64 s[4:5], vcc
	s_cbranch_execz .LBB0_15
	v_readfirstlane_b32 s100, v52
	s_nop 3
	v_lshlrev_b32_e32 v120, 4, v0
	v_lshlrev_b32_e32 v121, 3, v0
	v_lshlrev_b32_e32 v122, 2, v214
	v_lshlrev_b32_e32 v123, 2, v215
	v_lshlrev_b32_e32 v124, 2, v216
	v_lshlrev_b32_e32 v125, 2, v217
	v_lshlrev_b32_e32 v126, 2, v218
	v_lshlrev_b32_e32 v127, 2, v219
	s_lshl_b32 s2, s100, 17
	s_add_u32 s8, s8, s2
	s_addc_u32 s9, s9, 0
	s_add_u32 s6, s6, s2
	s_addc_u32 s7, s7, 0
	global_load_dwordx4 v[0:3], v120, s[10:11] offset:0
	global_load_dwordx4 v[4:7], v120, s[10:11] offset:1024
	global_load_dwordx4 v[8:11], v120, s[10:11] offset:2048
	global_load_dwordx4 v[12:15], v120, s[10:11] offset:3072
	s_movk_i32 s2, 8
.Lrms_final_loop:
	global_load_dwordx4 v[48:51], v120, s[8:9] offset:0
	global_load_dwordx4 v[52:55], v120, s[8:9] offset:1024
	global_load_dwordx4 v[56:59], v120, s[8:9] offset:2048
	global_load_dwordx4 v[60:63], v120, s[8:9] offset:3072
	s_add_u32 s8, s8, 0x1000
	s_addc_u32 s9, s9, 0
	global_load_dwordx4 v[64:67], v120, s[8:9] offset:0
	global_load_dwordx4 v[68:71], v120, s[8:9] offset:1024
	global_load_dwordx4 v[72:75], v120, s[8:9] offset:2048
	global_load_dwordx4 v[76:79], v120, s[8:9] offset:3072
	s_add_u32 s8, s8, 0x1000
	s_addc_u32 s9, s9, 0
	global_load_dwordx4 v[80:83], v120, s[8:9] offset:0
	global_load_dwordx4 v[84:87], v120, s[8:9] offset:1024
	global_load_dwordx4 v[88:91], v120, s[8:9] offset:2048
	global_load_dwordx4 v[92:95], v120, s[8:9] offset:3072
	s_add_u32 s8, s8, 0x1000
	s_addc_u32 s9, s9, 0
	global_load_dwordx4 v[96:99], v120, s[8:9] offset:0
	global_load_dwordx4 v[100:103], v120, s[8:9] offset:1024
	global_load_dwordx4 v[104:107], v120, s[8:9] offset:2048
	global_load_dwordx4 v[108:111], v120, s[8:9] offset:3072
	s_add_u32 s8, s8, 0x1000
	s_addc_u32 s9, s9, 0
	s_waitcnt vmcnt(12)
	v_mul_f32_e32 v112, v48, v48
	v_fmac_f32_e32 v112, v49, v49
	v_fmac_f32_e32 v112, v50, v50
	v_fmac_f32_e32 v112, v51, v51
	v_fmac_f32_e32 v112, v52, v52
	v_fmac_f32_e32 v112, v53, v53
	v_fmac_f32_e32 v112, v54, v54
	v_fmac_f32_e32 v112, v55, v55
	v_fmac_f32_e32 v112, v56, v56
	v_fmac_f32_e32 v112, v57, v57
	v_fmac_f32_e32 v112, v58, v58
	v_fmac_f32_e32 v112, v59, v59
	v_fmac_f32_e32 v112, v60, v60
	v_fmac_f32_e32 v112, v61, v61
	v_fmac_f32_e32 v112, v62, v62
	v_fmac_f32_e32 v112, v63, v63
	s_waitcnt vmcnt(8)
	v_mul_f32_e32 v113, v64, v64
	v_fmac_f32_e32 v113, v65, v65
	v_fmac_f32_e32 v113, v66, v66
	v_fmac_f32_e32 v113, v67, v67
	v_fmac_f32_e32 v113, v68, v68
	v_fmac_f32_e32 v113, v69, v69
	v_fmac_f32_e32 v113, v70, v70
	v_fmac_f32_e32 v113, v71, v71
	v_fmac_f32_e32 v113, v72, v72
	v_fmac_f32_e32 v113, v73, v73
	v_fmac_f32_e32 v113, v74, v74
	v_fmac_f32_e32 v113, v75, v75
	v_fmac_f32_e32 v113, v76, v76
	v_fmac_f32_e32 v113, v77, v77
	v_fmac_f32_e32 v113, v78, v78
	v_fmac_f32_e32 v113, v79, v79
	s_waitcnt vmcnt(4)
	v_mul_f32_e32 v114, v80, v80
	v_fmac_f32_e32 v114, v81, v81
	v_fmac_f32_e32 v114, v82, v82
	v_fmac_f32_e32 v114, v83, v83
	v_fmac_f32_e32 v114, v84, v84
	v_fmac_f32_e32 v114, v85, v85
	v_fmac_f32_e32 v114, v86, v86
	v_fmac_f32_e32 v114, v87, v87
	v_fmac_f32_e32 v114, v88, v88
	v_fmac_f32_e32 v114, v89, v89
	v_fmac_f32_e32 v114, v90, v90
	v_fmac_f32_e32 v114, v91, v91
	v_fmac_f32_e32 v114, v92, v92
	v_fmac_f32_e32 v114, v93, v93
	v_fmac_f32_e32 v114, v94, v94
	v_fmac_f32_e32 v114, v95, v95
	s_waitcnt vmcnt(0)
	v_mul_f32_e32 v115, v96, v96
	v_fmac_f32_e32 v115, v97, v97
	v_fmac_f32_e32 v115, v98, v98
	v_fmac_f32_e32 v115, v99, v99
	v_fmac_f32_e32 v115, v100, v100
	v_fmac_f32_e32 v115, v101, v101
	v_fmac_f32_e32 v115, v102, v102
	v_fmac_f32_e32 v115, v103, v103
	v_fmac_f32_e32 v115, v104, v104
	v_fmac_f32_e32 v115, v105, v105
	v_fmac_f32_e32 v115, v106, v106
	v_fmac_f32_e32 v115, v107, v107
	v_fmac_f32_e32 v115, v108, v108
	v_fmac_f32_e32 v115, v109, v109
	v_fmac_f32_e32 v115, v110, v110
	v_fmac_f32_e32 v115, v111, v111
	ds_bpermute_b32 v116, v122, v112
	ds_bpermute_b32 v117, v122, v113
	ds_bpermute_b32 v118, v122, v114
	ds_bpermute_b32 v119, v122, v115
	s_waitcnt lgkmcnt(0)
	v_add_f32_e32 v112, v112, v116
	v_add_f32_e32 v113, v113, v117
	v_add_f32_e32 v114, v114, v118
	v_add_f32_e32 v115, v115, v119
	ds_bpermute_b32 v116, v123, v112
	ds_bpermute_b32 v117, v123, v113
	ds_bpermute_b32 v118, v123, v114
	ds_bpermute_b32 v119, v123, v115
	s_waitcnt lgkmcnt(0)
	v_add_f32_e32 v112, v112, v116
	v_add_f32_e32 v113, v113, v117
	v_add_f32_e32 v114, v114, v118
	v_add_f32_e32 v115, v115, v119
	ds_bpermute_b32 v116, v124, v112
	ds_bpermute_b32 v117, v124, v113
	ds_bpermute_b32 v118, v124, v114
	ds_bpermute_b32 v119, v124, v115
	s_waitcnt lgkmcnt(0)
	v_add_f32_e32 v112, v112, v116
	v_add_f32_e32 v113, v113, v117
	v_add_f32_e32 v114, v114, v118
	v_add_f32_e32 v115, v115, v119
	ds_bpermute_b32 v116, v125, v112
	ds_bpermute_b32 v117, v125, v113
	ds_bpermute_b32 v118, v125, v114
	ds_bpermute_b32 v119, v125, v115
	s_waitcnt lgkmcnt(0)
	v_add_f32_e32 v112, v112, v116
	v_add_f32_e32 v113, v113, v117
	v_add_f32_e32 v114, v114, v118
	v_add_f32_e32 v115, v115, v119
	ds_bpermute_b32 v116, v126, v112
	ds_bpermute_b32 v117, v126, v113
	ds_bpermute_b32 v118, v126, v114
	ds_bpermute_b32 v119, v126, v115
	s_waitcnt lgkmcnt(0)
	v_add_f32_e32 v112, v112, v116
	v_add_f32_e32 v113, v113, v117
	v_add_f32_e32 v114, v114, v118
	v_add_f32_e32 v115, v115, v119
	ds_bpermute_b32 v116, v127, v112
	ds_bpermute_b32 v117, v127, v113
	ds_bpermute_b32 v118, v127, v114
	ds_bpermute_b32 v119, v127, v115
	s_waitcnt lgkmcnt(0)
	v_add_f32_e32 v112, v112, v116
	v_add_f32_e32 v113, v113, v117
	v_add_f32_e32 v114, v114, v118
	v_add_f32_e32 v115, v115, v119
	v_fmamk_f32 v112, v112, 0x3a800000, v208
	v_fmamk_f32 v113, v113, 0x3a800000, v208
	v_fmamk_f32 v114, v114, 0x3a800000, v208
	v_fmamk_f32 v115, v115, 0x3a800000, v208
	v_rsq_f32_e32 v112, v112
	v_rsq_f32_e32 v113, v113
	v_rsq_f32_e32 v114, v114
	v_rsq_f32_e32 v115, v115
	s_nop 1
	v_mul_f32_e32 v48, v48, v112
	v_mul_f32_e32 v49, v49, v112
	v_mul_f32_e32 v50, v50, v112
	v_mul_f32_e32 v51, v51, v112
	v_mul_f32_e32 v48, v0, v48
	v_mul_f32_e32 v49, v1, v49
	v_mul_f32_e32 v50, v2, v50
	v_mul_f32_e32 v51, v3, v51
	global_store_dwordx4 v120, v[48:51], s[6:7] offset:0
	v_mul_f32_e32 v52, v52, v112
	v_mul_f32_e32 v53, v53, v112
	v_mul_f32_e32 v54, v54, v112
	v_mul_f32_e32 v55, v55, v112
	v_mul_f32_e32 v52, v4, v52
	v_mul_f32_e32 v53, v5, v53
	v_mul_f32_e32 v54, v6, v54
	v_mul_f32_e32 v55, v7, v55
	global_store_dwordx4 v120, v[52:55], s[6:7] offset:1024
	v_mul_f32_e32 v56, v56, v112
	v_mul_f32_e32 v57, v57, v112
	v_mul_f32_e32 v58, v58, v112
	v_mul_f32_e32 v59, v59, v112
	v_mul_f32_e32 v56, v8, v56
	v_mul_f32_e32 v57, v9, v57
	v_mul_f32_e32 v58, v10, v58
	v_mul_f32_e32 v59, v11, v59
	global_store_dwordx4 v120, v[56:59], s[6:7] offset:2048
	v_mul_f32_e32 v60, v60, v112
	v_mul_f32_e32 v61, v61, v112
	v_mul_f32_e32 v62, v62, v112
	v_mul_f32_e32 v63, v63, v112
	v_mul_f32_e32 v60, v12, v60
	v_mul_f32_e32 v61, v13, v61
	v_mul_f32_e32 v62, v14, v62
	v_mul_f32_e32 v63, v15, v63
	global_store_dwordx4 v120, v[60:63], s[6:7] offset:3072
	s_add_u32 s6, s6, 0x1000
	s_addc_u32 s7, s7, 0
	v_mul_f32_e32 v64, v64, v113
	v_mul_f32_e32 v65, v65, v113
	v_mul_f32_e32 v66, v66, v113
	v_mul_f32_e32 v67, v67, v113
	v_mul_f32_e32 v64, v0, v64
	v_mul_f32_e32 v65, v1, v65
	v_mul_f32_e32 v66, v2, v66
	v_mul_f32_e32 v67, v3, v67
	global_store_dwordx4 v120, v[64:67], s[6:7] offset:0
	v_mul_f32_e32 v68, v68, v113
	v_mul_f32_e32 v69, v69, v113
	v_mul_f32_e32 v70, v70, v113
	v_mul_f32_e32 v71, v71, v113
	v_mul_f32_e32 v68, v4, v68
	v_mul_f32_e32 v69, v5, v69
	v_mul_f32_e32 v70, v6, v70
	v_mul_f32_e32 v71, v7, v71
	global_store_dwordx4 v120, v[68:71], s[6:7] offset:1024
	v_mul_f32_e32 v72, v72, v113
	v_mul_f32_e32 v73, v73, v113
	v_mul_f32_e32 v74, v74, v113
	v_mul_f32_e32 v75, v75, v113
	v_mul_f32_e32 v72, v8, v72
	v_mul_f32_e32 v73, v9, v73
	v_mul_f32_e32 v74, v10, v74
	v_mul_f32_e32 v75, v11, v75
	global_store_dwordx4 v120, v[72:75], s[6:7] offset:2048
	v_mul_f32_e32 v76, v76, v113
	v_mul_f32_e32 v77, v77, v113
	v_mul_f32_e32 v78, v78, v113
	v_mul_f32_e32 v79, v79, v113
	v_mul_f32_e32 v76, v12, v76
	v_mul_f32_e32 v77, v13, v77
	v_mul_f32_e32 v78, v14, v78
	v_mul_f32_e32 v79, v15, v79
	global_store_dwordx4 v120, v[76:79], s[6:7] offset:3072
	s_add_u32 s6, s6, 0x1000
	s_addc_u32 s7, s7, 0
	v_mul_f32_e32 v80, v80, v114
	v_mul_f32_e32 v81, v81, v114
	v_mul_f32_e32 v82, v82, v114
	v_mul_f32_e32 v83, v83, v114
	v_mul_f32_e32 v80, v0, v80
	v_mul_f32_e32 v81, v1, v81
	v_mul_f32_e32 v82, v2, v82
	v_mul_f32_e32 v83, v3, v83
	global_store_dwordx4 v120, v[80:83], s[6:7] offset:0
	v_mul_f32_e32 v84, v84, v114
	v_mul_f32_e32 v85, v85, v114
	v_mul_f32_e32 v86, v86, v114
	v_mul_f32_e32 v87, v87, v114
	v_mul_f32_e32 v84, v4, v84
	v_mul_f32_e32 v85, v5, v85
	v_mul_f32_e32 v86, v6, v86
	v_mul_f32_e32 v87, v7, v87
	global_store_dwordx4 v120, v[84:87], s[6:7] offset:1024
	v_mul_f32_e32 v88, v88, v114
	v_mul_f32_e32 v89, v89, v114
	v_mul_f32_e32 v90, v90, v114
	v_mul_f32_e32 v91, v91, v114
	v_mul_f32_e32 v88, v8, v88
	v_mul_f32_e32 v89, v9, v89
	v_mul_f32_e32 v90, v10, v90
	v_mul_f32_e32 v91, v11, v91
	global_store_dwordx4 v120, v[88:91], s[6:7] offset:2048
	v_mul_f32_e32 v92, v92, v114
	v_mul_f32_e32 v93, v93, v114
	v_mul_f32_e32 v94, v94, v114
	v_mul_f32_e32 v95, v95, v114
	v_mul_f32_e32 v92, v12, v92
	v_mul_f32_e32 v93, v13, v93
	v_mul_f32_e32 v94, v14, v94
	v_mul_f32_e32 v95, v15, v95
	global_store_dwordx4 v120, v[92:95], s[6:7] offset:3072
	s_add_u32 s6, s6, 0x1000
	s_addc_u32 s7, s7, 0
	v_mul_f32_e32 v96, v96, v115
	v_mul_f32_e32 v97, v97, v115
	v_mul_f32_e32 v98, v98, v115
	v_mul_f32_e32 v99, v99, v115
	v_mul_f32_e32 v96, v0, v96
	v_mul_f32_e32 v97, v1, v97
	v_mul_f32_e32 v98, v2, v98
	v_mul_f32_e32 v99, v3, v99
	global_store_dwordx4 v120, v[96:99], s[6:7] offset:0
	v_mul_f32_e32 v100, v100, v115
	v_mul_f32_e32 v101, v101, v115
	v_mul_f32_e32 v102, v102, v115
	v_mul_f32_e32 v103, v103, v115
	v_mul_f32_e32 v100, v4, v100
	v_mul_f32_e32 v101, v5, v101
	v_mul_f32_e32 v102, v6, v102
	v_mul_f32_e32 v103, v7, v103
	global_store_dwordx4 v120, v[100:103], s[6:7] offset:1024
	v_mul_f32_e32 v104, v104, v115
	v_mul_f32_e32 v105, v105, v115
	v_mul_f32_e32 v106, v106, v115
	v_mul_f32_e32 v107, v107, v115
	v_mul_f32_e32 v104, v8, v104
	v_mul_f32_e32 v105, v9, v105
	v_mul_f32_e32 v106, v10, v106
	v_mul_f32_e32 v107, v11, v107
	global_store_dwordx4 v120, v[104:107], s[6:7] offset:2048
	v_mul_f32_e32 v108, v108, v115
	v_mul_f32_e32 v109, v109, v115
	v_mul_f32_e32 v110, v110, v115
	v_mul_f32_e32 v111, v111, v115
	v_mul_f32_e32 v108, v12, v108
	v_mul_f32_e32 v109, v13, v109
	v_mul_f32_e32 v110, v14, v110
	v_mul_f32_e32 v111, v15, v111
	global_store_dwordx4 v120, v[108:111], s[6:7] offset:3072
	s_add_u32 s6, s6, 0x1000
	s_addc_u32 s7, s7, 0
	s_sub_u32 s2, s2, 1
	s_cmp_lg_u32 s2, 0
	s_cbranch_scc1 .Lrms_final_loop

.LBB0_83:
	v_writelane_b32 v252, s4, 35
	s_and_b64 vcc, exec, s[8:9]
	s_nop 0
	v_writelane_b32 v252, s5, 36
	s_cbranch_vccz .LBB0_90
	v_mov_b32_e32 v0, 0xe0
	v_readlane_b32 s4, v253, 11
	v_add_u32_e32 v0, s91, v0
	ds_read_b64 v[0:1], v0
	s_waitcnt lgkmcnt(0)
	v_readfirstlane_b32 s6, v0
	v_mov_b32_e32 v0, 24
	v_readfirstlane_b32 s7, v1
	v_add_u32_e32 v0, s91, v0
	ds_read_b64 v[0:1], v0
	s_waitcnt lgkmcnt(0)
	v_readfirstlane_b32 s10, v0
	v_mov_b32_e32 v0, 0xe8
	v_readfirstlane_b32 s2, v1
	v_add_u32_e32 v0, s91, v0
	ds_read_b64 v[0:1], v0
	s_waitcnt lgkmcnt(0)
	v_readfirstlane_b32 s9, v1
	v_readfirstlane_b32 s8, v0
	v_mbcnt_lo_u32_b32 v0, -1, 0
	v_mbcnt_hi_u32_b32 v0, -1, v0
	s_nop 0
	v_add_u32_e32 v1, s57, v0
	v_ashrrev_i32_e32 v1, 6, v1
	v_add_u32_e32 v56, s4, v1
	v_cmp_gt_i32_e32 vcc, s3, v56
	s_and_saveexec_b64 s[4:5], vcc
	v_readlane_b32 s14, v252, 23
	s_cbranch_execz .LBB0_89
	v_readfirstlane_b32 s100, v56
	v_readlane_b32 s11, v252, 31
	s_nop 3
	s_lshl_b32 s12, s11, 12
	s_mov_b32 s11, s2
	s_add_u32 s10, s10, s12
	s_addc_u32 s11, s11, 0
	s_add_u32 s8, s8, 0x5200000
	s_addc_u32 s9, s9, 0
	s_nop 3
	v_lshlrev_b32_e32 v120, 4, v0
	v_lshlrev_b32_e32 v121, 3, v0
	v_lshlrev_b32_e32 v122, 2, v214
	v_lshlrev_b32_e32 v123, 2, v215
	v_lshlrev_b32_e32 v124, 2, v216
	v_lshlrev_b32_e32 v125, 2, v217
	v_lshlrev_b32_e32 v126, 2, v218
	v_lshlrev_b32_e32 v127, 2, v219
	s_lshl_b32 s2, s100, 17
	s_add_u32 s6, s6, s2
	s_addc_u32 s7, s7, 0
	s_lshl_b32 s2, s100, 16
	s_add_u32 s8, s8, s2
	s_addc_u32 s9, s9, 0
	global_load_dwordx4 v[0:3], v120, s[10:11] offset:0
	global_load_dwordx4 v[4:7], v120, s[10:11] offset:1024
	global_load_dwordx4 v[8:11], v120, s[10:11] offset:2048
	global_load_dwordx4 v[12:15], v120, s[10:11] offset:3072
	v_readlane_b32 s10, v252, 32
	v_readlane_b32 s11, v252, 33
	s_lshr_b32 s2, s100, 6
	s_mul_i32 s2, s2, 0x6000
	s_nop 3
	s_add_u32 s10, s10, s2
	s_addc_u32 s11, s11, 0
	s_add_u32 s10, s10, 0x4000
	s_addc_u32 s11, s11, 0
	global_load_dwordx4 v[16:19], v120, s[10:11] offset:0
	global_load_dwordx4 v[20:23], v120, s[10:11] offset:1024
	global_load_dwordx4 v[24:27], v120, s[10:11] offset:2048
	global_load_dwordx4 v[28:31], v120, s[10:11] offset:3072
	s_sub_u32 s10, s10, 0x1000
	s_subb_u32 s11, s11, 0
	global_load_dwordx4 v[32:35], v120, s[10:11] offset:0
	global_load_dwordx4 v[36:39], v120, s[10:11] offset:1024
	global_load_dwordx4 v[40:43], v120, s[10:11] offset:2048
	global_load_dwordx4 v[44:47], v120, s[10:11] offset:3072
	s_waitcnt vmcnt(0)
	v_add_f32_e32 v16, 1.0, v16
	v_add_f32_e32 v17, 1.0, v17
	v_add_f32_e32 v18, 1.0, v18
	v_add_f32_e32 v19, 1.0, v19
	v_add_f32_e32 v20, 1.0, v20
	v_add_f32_e32 v21, 1.0, v21
	v_add_f32_e32 v22, 1.0, v22
	v_add_f32_e32 v23, 1.0, v23
	v_add_f32_e32 v24, 1.0, v24
	v_add_f32_e32 v25, 1.0, v25
	v_add_f32_e32 v26, 1.0, v26
	v_add_f32_e32 v27, 1.0, v27
	v_add_f32_e32 v28, 1.0, v28
	v_add_f32_e32 v29, 1.0, v29
	v_add_f32_e32 v30, 1.0, v30
	v_add_f32_e32 v31, 1.0, v31
	s_movk_i32 s2, 8
.Lrms_sub6_loop:
	global_load_dwordx4 v[48:51], v120, s[6:7] offset:0
	global_load_dwordx4 v[52:55], v120, s[6:7] offset:1024
	global_load_dwordx4 v[56:59], v120, s[6:7] offset:2048
	global_load_dwordx4 v[60:63], v120, s[6:7] offset:3072
	s_add_u32 s6, s6, 0x1000
	s_addc_u32 s7, s7, 0
	global_load_dwordx4 v[64:67], v120, s[6:7] offset:0
	global_load_dwordx4 v[68:71], v120, s[6:7] offset:1024
	global_load_dwordx4 v[72:75], v120, s[6:7] offset:2048
	global_load_dwordx4 v[76:79], v120, s[6:7] offset:3072
	s_add_u32 s6, s6, 0x1000
	s_addc_u32 s7, s7, 0
	global_load_dwordx4 v[80:83], v120, s[6:7] offset:0
	global_load_dwordx4 v[84:87], v120, s[6:7] offset:1024
	global_load_dwordx4 v[88:91], v120, s[6:7] offset:2048
	global_load_dwordx4 v[92:95], v120, s[6:7] offset:3072
	s_add_u32 s6, s6, 0x1000
	s_addc_u32 s7, s7, 0
	global_load_dwordx4 v[96:99], v120, s[6:7] offset:0
	global_load_dwordx4 v[100:103], v120, s[6:7] offset:1024
	global_load_dwordx4 v[104:107], v120, s[6:7] offset:2048
	global_load_dwordx4 v[108:111], v120, s[6:7] offset:3072
	s_add_u32 s6, s6, 0x1000
	s_addc_u32 s7, s7, 0
	s_waitcnt vmcnt(12)
	v_mul_f32_e32 v112, v48, v48
	v_fmac_f32_e32 v112, v49, v49
	v_fmac_f32_e32 v112, v50, v50
	v_fmac_f32_e32 v112, v51, v51
	v_fmac_f32_e32 v112, v52, v52
	v_fmac_f32_e32 v112, v53, v53
	v_fmac_f32_e32 v112, v54, v54
	v_fmac_f32_e32 v112, v55, v55
	v_fmac_f32_e32 v112, v56, v56
	v_fmac_f32_e32 v112, v57, v57
	v_fmac_f32_e32 v112, v58, v58
	v_fmac_f32_e32 v112, v59, v59
	v_fmac_f32_e32 v112, v60, v60
	v_fmac_f32_e32 v112, v61, v61
	v_fmac_f32_e32 v112, v62, v62
	v_fmac_f32_e32 v112, v63, v63
	s_waitcnt vmcnt(8)
	v_mul_f32_e32 v113, v64, v64
	v_fmac_f32_e32 v113, v65, v65
	v_fmac_f32_e32 v113, v66, v66
	v_fmac_f32_e32 v113, v67, v67
	v_fmac_f32_e32 v113, v68, v68
	v_fmac_f32_e32 v113, v69, v69
	v_fmac_f32_e32 v113, v70, v70
	v_fmac_f32_e32 v113, v71, v71
	v_fmac_f32_e32 v113, v72, v72
	v_fmac_f32_e32 v113, v73, v73
	v_fmac_f32_e32 v113, v74, v74
	v_fmac_f32_e32 v113, v75, v75
	v_fmac_f32_e32 v113, v76, v76
	v_fmac_f32_e32 v113, v77, v77
	v_fmac_f32_e32 v113, v78, v78
	v_fmac_f32_e32 v113, v79, v79
	s_waitcnt vmcnt(4)
	v_mul_f32_e32 v114, v80, v80
	v_fmac_f32_e32 v114, v81, v81
	v_fmac_f32_e32 v114, v82, v82
	v_fmac_f32_e32 v114, v83, v83
	v_fmac_f32_e32 v114, v84, v84
	v_fmac_f32_e32 v114, v85, v85
	v_fmac_f32_e32 v114, v86, v86
	v_fmac_f32_e32 v114, v87, v87
	v_fmac_f32_e32 v114, v88, v88
	v_fmac_f32_e32 v114, v89, v89
	v_fmac_f32_e32 v114, v90, v90
	v_fmac_f32_e32 v114, v91, v91
	v_fmac_f32_e32 v114, v92, v92
	v_fmac_f32_e32 v114, v93, v93
	v_fmac_f32_e32 v114, v94, v94
	v_fmac_f32_e32 v114, v95, v95
	s_waitcnt vmcnt(0)
	v_mul_f32_e32 v115, v96, v96
	v_fmac_f32_e32 v115, v97, v97
	v_fmac_f32_e32 v115, v98, v98
	v_fmac_f32_e32 v115, v99, v99
	v_fmac_f32_e32 v115, v100, v100
	v_fmac_f32_e32 v115, v101, v101
	v_fmac_f32_e32 v115, v102, v102
	v_fmac_f32_e32 v115, v103, v103
	v_fmac_f32_e32 v115, v104, v104
	v_fmac_f32_e32 v115, v105, v105
	v_fmac_f32_e32 v115, v106, v106
	v_fmac_f32_e32 v115, v107, v107
	v_fmac_f32_e32 v115, v108, v108
	v_fmac_f32_e32 v115, v109, v109
	v_fmac_f32_e32 v115, v110, v110
	v_fmac_f32_e32 v115, v111, v111
	ds_bpermute_b32 v116, v122, v112
	ds_bpermute_b32 v117, v122, v113
	ds_bpermute_b32 v118, v122, v114
	ds_bpermute_b32 v119, v122, v115
	s_waitcnt lgkmcnt(0)
	v_add_f32_e32 v112, v112, v116
	v_add_f32_e32 v113, v113, v117
	v_add_f32_e32 v114, v114, v118
	v_add_f32_e32 v115, v115, v119
	ds_bpermute_b32 v116, v123, v112
	ds_bpermute_b32 v117, v123, v113
	ds_bpermute_b32 v118, v123, v114
	ds_bpermute_b32 v119, v123, v115
	s_waitcnt lgkmcnt(0)
	v_add_f32_e32 v112, v112, v116
	v_add_f32_e32 v113, v113, v117
	v_add_f32_e32 v114, v114, v118
	v_add_f32_e32 v115, v115, v119
	ds_bpermute_b32 v116, v124, v112
	ds_bpermute_b32 v117, v124, v113
	ds_bpermute_b32 v118, v124, v114
	ds_bpermute_b32 v119, v124, v115
	s_waitcnt lgkmcnt(0)
	v_add_f32_e32 v112, v112, v116
	v_add_f32_e32 v113, v113, v117
	v_add_f32_e32 v114, v114, v118
	v_add_f32_e32 v115, v115, v119
	ds_bpermute_b32 v116, v125, v112
	ds_bpermute_b32 v117, v125, v113
	ds_bpermute_b32 v118, v125, v114
	ds_bpermute_b32 v119, v125, v115
	s_waitcnt lgkmcnt(0)
	v_add_f32_e32 v112, v112, v116
	v_add_f32_e32 v113, v113, v117
	v_add_f32_e32 v114, v114, v118
	v_add_f32_e32 v115, v115, v119
	ds_bpermute_b32 v116, v126, v112
	ds_bpermute_b32 v117, v126, v113
	ds_bpermute_b32 v118, v126, v114
	ds_bpermute_b32 v119, v126, v115
	s_waitcnt lgkmcnt(0)
	v_add_f32_e32 v112, v112, v116
	v_add_f32_e32 v113, v113, v117
	v_add_f32_e32 v114, v114, v118
	v_add_f32_e32 v115, v115, v119
	ds_bpermute_b32 v116, v127, v112
	ds_bpermute_b32 v117, v127, v113
	ds_bpermute_b32 v118, v127, v114
	ds_bpermute_b32 v119, v127, v115
	s_waitcnt lgkmcnt(0)
	v_add_f32_e32 v112, v112, v116
	v_add_f32_e32 v113, v113, v117
	v_add_f32_e32 v114, v114, v118
	v_add_f32_e32 v115, v115, v119
	v_fmamk_f32 v112, v112, 0x3a800000, v208
	v_fmamk_f32 v113, v113, 0x3a800000, v208
	v_fmamk_f32 v114, v114, 0x3a800000, v208
	v_fmamk_f32 v115, v115, 0x3a800000, v208
	v_rsq_f32_e32 v112, v112
	v_rsq_f32_e32 v113, v113
	v_rsq_f32_e32 v114, v114
	v_rsq_f32_e32 v115, v115
	s_nop 1
	v_mul_f32_e32 v48, v48, v112
	v_mul_f32_e32 v49, v49, v112
	v_mul_f32_e32 v50, v50, v112
	v_mul_f32_e32 v51, v51, v112
	v_mul_f32_e32 v48, v0, v48
	v_mul_f32_e32 v49, v1, v49
	v_mul_f32_e32 v50, v2, v50
	v_mul_f32_e32 v51, v3, v51
	v_fma_f32 v48, v48, v16, v32
	v_fma_f32 v49, v49, v17, v33
	v_fma_f32 v50, v50, v18, v34
	v_fma_f32 v51, v51, v19, v35
	v_cvt_pk_bf16_f32 v128, v48, v49
	v_cvt_pk_bf16_f32 v129, v50, v51
	global_store_dwordx2 v121, v[128:129], s[8:9] offset:0
	v_mul_f32_e32 v52, v52, v112
	v_mul_f32_e32 v53, v53, v112
	v_mul_f32_e32 v54, v54, v112
	v_mul_f32_e32 v55, v55, v112
	v_mul_f32_e32 v52, v4, v52
	v_mul_f32_e32 v53, v5, v53
	v_mul_f32_e32 v54, v6, v54
	v_mul_f32_e32 v55, v7, v55
	v_fma_f32 v52, v52, v20, v36
	v_fma_f32 v53, v53, v21, v37
	v_fma_f32 v54, v54, v22, v38
	v_fma_f32 v55, v55, v23, v39
	v_cvt_pk_bf16_f32 v130, v52, v53
	v_cvt_pk_bf16_f32 v131, v54, v55
	global_store_dwordx2 v121, v[130:131], s[8:9] offset:512
	v_mul_f32_e32 v56, v56, v112
	v_mul_f32_e32 v57, v57, v112
	v_mul_f32_e32 v58, v58, v112
	v_mul_f32_e32 v59, v59, v112
	v_mul_f32_e32 v56, v8, v56
	v_mul_f32_e32 v57, v9, v57
	v_mul_f32_e32 v58, v10, v58
	v_mul_f32_e32 v59, v11, v59
	v_fma_f32 v56, v56, v24, v40
	v_fma_f32 v57, v57, v25, v41
	v_fma_f32 v58, v58, v26, v42
	v_fma_f32 v59, v59, v27, v43
	v_cvt_pk_bf16_f32 v128, v56, v57
	v_cvt_pk_bf16_f32 v129, v58, v59
	global_store_dwordx2 v121, v[128:129], s[8:9] offset:1024
	v_mul_f32_e32 v60, v60, v112
	v_mul_f32_e32 v61, v61, v112
	v_mul_f32_e32 v62, v62, v112
	v_mul_f32_e32 v63, v63, v112
	v_mul_f32_e32 v60, v12, v60
	v_mul_f32_e32 v61, v13, v61
	v_mul_f32_e32 v62, v14, v62
	v_mul_f32_e32 v63, v15, v63
	v_fma_f32 v60, v60, v28, v44
	v_fma_f32 v61, v61, v29, v45
	v_fma_f32 v62, v62, v30, v46
	v_fma_f32 v63, v63, v31, v47
	v_cvt_pk_bf16_f32 v130, v60, v61
	v_cvt_pk_bf16_f32 v131, v62, v63
	global_store_dwordx2 v121, v[130:131], s[8:9] offset:1536
	s_add_u32 s8, s8, 0x800
	s_addc_u32 s9, s9, 0
	v_mul_f32_e32 v64, v64, v113
	v_mul_f32_e32 v65, v65, v113
	v_mul_f32_e32 v66, v66, v113
	v_mul_f32_e32 v67, v67, v113
	v_mul_f32_e32 v64, v0, v64
	v_mul_f32_e32 v65, v1, v65
	v_mul_f32_e32 v66, v2, v66
	v_mul_f32_e32 v67, v3, v67
	v_fma_f32 v64, v64, v16, v32
	v_fma_f32 v65, v65, v17, v33
	v_fma_f32 v66, v66, v18, v34
	v_fma_f32 v67, v67, v19, v35
	v_cvt_pk_bf16_f32 v128, v64, v65
	v_cvt_pk_bf16_f32 v129, v66, v67
	global_store_dwordx2 v121, v[128:129], s[8:9] offset:0
	v_mul_f32_e32 v68, v68, v113
	v_mul_f32_e32 v69, v69, v113
	v_mul_f32_e32 v70, v70, v113
	v_mul_f32_e32 v71, v71, v113
	v_mul_f32_e32 v68, v4, v68
	v_mul_f32_e32 v69, v5, v69
	v_mul_f32_e32 v70, v6, v70
	v_mul_f32_e32 v71, v7, v71
	v_fma_f32 v68, v68, v20, v36
	v_fma_f32 v69, v69, v21, v37
	v_fma_f32 v70, v70, v22, v38
	v_fma_f32 v71, v71, v23, v39
	v_cvt_pk_bf16_f32 v130, v68, v69
	v_cvt_pk_bf16_f32 v131, v70, v71
	global_store_dwordx2 v121, v[130:131], s[8:9] offset:512
	v_mul_f32_e32 v72, v72, v113
	v_mul_f32_e32 v73, v73, v113
	v_mul_f32_e32 v74, v74, v113
	v_mul_f32_e32 v75, v75, v113
	v_mul_f32_e32 v72, v8, v72
	v_mul_f32_e32 v73, v9, v73
	v_mul_f32_e32 v74, v10, v74
	v_mul_f32_e32 v75, v11, v75
	v_fma_f32 v72, v72, v24, v40
	v_fma_f32 v73, v73, v25, v41
	v_fma_f32 v74, v74, v26, v42
	v_fma_f32 v75, v75, v27, v43
	v_cvt_pk_bf16_f32 v128, v72, v73
	v_cvt_pk_bf16_f32 v129, v74, v75
	global_store_dwordx2 v121, v[128:129], s[8:9] offset:1024
	v_mul_f32_e32 v76, v76, v113
	v_mul_f32_e32 v77, v77, v113
	v_mul_f32_e32 v78, v78, v113
	v_mul_f32_e32 v79, v79, v113
	v_mul_f32_e32 v76, v12, v76
	v_mul_f32_e32 v77, v13, v77
	v_mul_f32_e32 v78, v14, v78
	v_mul_f32_e32 v79, v15, v79
	v_fma_f32 v76, v76, v28, v44
	v_fma_f32 v77, v77, v29, v45
	v_fma_f32 v78, v78, v30, v46
	v_fma_f32 v79, v79, v31, v47
	v_cvt_pk_bf16_f32 v130, v76, v77
	v_cvt_pk_bf16_f32 v131, v78, v79
	global_store_dwordx2 v121, v[130:131], s[8:9] offset:1536
	s_add_u32 s8, s8, 0x800
	s_addc_u32 s9, s9, 0
	v_mul_f32_e32 v80, v80, v114
	v_mul_f32_e32 v81, v81, v114
	v_mul_f32_e32 v82, v82, v114
	v_mul_f32_e32 v83, v83, v114
	v_mul_f32_e32 v80, v0, v80
	v_mul_f32_e32 v81, v1, v81
	v_mul_f32_e32 v82, v2, v82
	v_mul_f32_e32 v83, v3, v83
	v_fma_f32 v80, v80, v16, v32
	v_fma_f32 v81, v81, v17, v33
	v_fma_f32 v82, v82, v18, v34
	v_fma_f32 v83, v83, v19, v35
	v_cvt_pk_bf16_f32 v128, v80, v81
	v_cvt_pk_bf16_f32 v129, v82, v83
	global_store_dwordx2 v121, v[128:129], s[8:9] offset:0
	v_mul_f32_e32 v84, v84, v114
	v_mul_f32_e32 v85, v85, v114
	v_mul_f32_e32 v86, v86, v114
	v_mul_f32_e32 v87, v87, v114
	v_mul_f32_e32 v84, v4, v84
	v_mul_f32_e32 v85, v5, v85
	v_mul_f32_e32 v86, v6, v86
	v_mul_f32_e32 v87, v7, v87
	v_fma_f32 v84, v84, v20, v36
	v_fma_f32 v85, v85, v21, v37
	v_fma_f32 v86, v86, v22, v38
	v_fma_f32 v87, v87, v23, v39
	v_cvt_pk_bf16_f32 v130, v84, v85
	v_cvt_pk_bf16_f32 v131, v86, v87
	global_store_dwordx2 v121, v[130:131], s[8:9] offset:512
	v_mul_f32_e32 v88, v88, v114
	v_mul_f32_e32 v89, v89, v114
	v_mul_f32_e32 v90, v90, v114
	v_mul_f32_e32 v91, v91, v114
	v_mul_f32_e32 v88, v8, v88
	v_mul_f32_e32 v89, v9, v89
	v_mul_f32_e32 v90, v10, v90
	v_mul_f32_e32 v91, v11, v91
	v_fma_f32 v88, v88, v24, v40
	v_fma_f32 v89, v89, v25, v41
	v_fma_f32 v90, v90, v26, v42
	v_fma_f32 v91, v91, v27, v43
	v_cvt_pk_bf16_f32 v128, v88, v89
	v_cvt_pk_bf16_f32 v129, v90, v91
	global_store_dwordx2 v121, v[128:129], s[8:9] offset:1024
	v_mul_f32_e32 v92, v92, v114
	v_mul_f32_e32 v93, v93, v114
	v_mul_f32_e32 v94, v94, v114
	v_mul_f32_e32 v95, v95, v114
	v_mul_f32_e32 v92, v12, v92
	v_mul_f32_e32 v93, v13, v93
	v_mul_f32_e32 v94, v14, v94
	v_mul_f32_e32 v95, v15, v95
	v_fma_f32 v92, v92, v28, v44
	v_fma_f32 v93, v93, v29, v45
	v_fma_f32 v94, v94, v30, v46
	v_fma_f32 v95, v95, v31, v47
	v_cvt_pk_bf16_f32 v130, v92, v93
	v_cvt_pk_bf16_f32 v131, v94, v95
	global_store_dwordx2 v121, v[130:131], s[8:9] offset:1536
	s_add_u32 s8, s8, 0x800
	s_addc_u32 s9, s9, 0
	v_mul_f32_e32 v96, v96, v115
	v_mul_f32_e32 v97, v97, v115
	v_mul_f32_e32 v98, v98, v115
	v_mul_f32_e32 v99, v99, v115
	v_mul_f32_e32 v96, v0, v96
	v_mul_f32_e32 v97, v1, v97
	v_mul_f32_e32 v98, v2, v98
	v_mul_f32_e32 v99, v3, v99
	v_fma_f32 v96, v96, v16, v32
	v_fma_f32 v97, v97, v17, v33
	v_fma_f32 v98, v98, v18, v34
	v_fma_f32 v99, v99, v19, v35
	v_cvt_pk_bf16_f32 v128, v96, v97
	v_cvt_pk_bf16_f32 v129, v98, v99
	global_store_dwordx2 v121, v[128:129], s[8:9] offset:0
	v_mul_f32_e32 v100, v100, v115
	v_mul_f32_e32 v101, v101, v115
	v_mul_f32_e32 v102, v102, v115
	v_mul_f32_e32 v103, v103, v115
	v_mul_f32_e32 v100, v4, v100
	v_mul_f32_e32 v101, v5, v101
	v_mul_f32_e32 v102, v6, v102
	v_mul_f32_e32 v103, v7, v103
	v_fma_f32 v100, v100, v20, v36
	v_fma_f32 v101, v101, v21, v37
	v_fma_f32 v102, v102, v22, v38
	v_fma_f32 v103, v103, v23, v39
	v_cvt_pk_bf16_f32 v130, v100, v101
	v_cvt_pk_bf16_f32 v131, v102, v103
	global_store_dwordx2 v121, v[130:131], s[8:9] offset:512
	v_mul_f32_e32 v104, v104, v115
	v_mul_f32_e32 v105, v105, v115
	v_mul_f32_e32 v106, v106, v115
	v_mul_f32_e32 v107, v107, v115
	v_mul_f32_e32 v104, v8, v104
	v_mul_f32_e32 v105, v9, v105
	v_mul_f32_e32 v106, v10, v106
	v_mul_f32_e32 v107, v11, v107
	v_fma_f32 v104, v104, v24, v40
	v_fma_f32 v105, v105, v25, v41
	v_fma_f32 v106, v106, v26, v42
	v_fma_f32 v107, v107, v27, v43
	v_cvt_pk_bf16_f32 v128, v104, v105
	v_cvt_pk_bf16_f32 v129, v106, v107
	global_store_dwordx2 v121, v[128:129], s[8:9] offset:1024
	v_mul_f32_e32 v108, v108, v115
	v_mul_f32_e32 v109, v109, v115
	v_mul_f32_e32 v110, v110, v115
	v_mul_f32_e32 v111, v111, v115
	v_mul_f32_e32 v108, v12, v108
	v_mul_f32_e32 v109, v13, v109
	v_mul_f32_e32 v110, v14, v110
	v_mul_f32_e32 v111, v15, v111
	v_fma_f32 v108, v108, v28, v44
	v_fma_f32 v109, v109, v29, v45
	v_fma_f32 v110, v110, v30, v46
	v_fma_f32 v111, v111, v31, v47
	v_cvt_pk_bf16_f32 v130, v108, v109
	v_cvt_pk_bf16_f32 v131, v110, v111
	global_store_dwordx2 v121, v[130:131], s[8:9] offset:1536
	s_add_u32 s8, s8, 0x800
	s_addc_u32 s9, s9, 0
	s_sub_u32 s2, s2, 1
	s_cmp_lg_u32 s2, 0
	s_cbranch_scc1 .Lrms_sub6_loop

.LBB0_562:
	s_and_b64 vcc, exec, s[0:1]
	s_cbranch_vccz .LBB0_569
	v_mov_b32_e32 v0, 16
	v_mov_b32_e32 v2, 0xe8
	v_add_u32_e32 v0, s91, v0
	ds_read_b64 v[0:1], v0
	v_readlane_b32 s0, v253, 11
	v_add_u32_e32 v2, s91, v2
	ds_read_b64 v[2:3], v2
	s_waitcnt lgkmcnt(0)
	v_readfirstlane_b32 s2, v1
	v_readfirstlane_b32 s6, v0
	v_mbcnt_lo_u32_b32 v0, -1, 0
	v_mbcnt_hi_u32_b32 v0, -1, v0
	v_readfirstlane_b32 s5, v3
	v_add_u32_e32 v1, s57, v0
	v_ashrrev_i32_e32 v1, 6, v1
	v_add_u32_e32 v52, s0, v1
	v_readfirstlane_b32 s4, v2
	v_cmp_gt_i32_e32 vcc, s3, v52
	s_and_saveexec_b64 s[0:1], vcc
	v_readlane_b32 s10, v252, 23
	s_cbranch_execz .LBB0_568
	v_readfirstlane_b32 s100, v52
	v_readlane_b32 s7, v252, 31
	s_nop 3
	s_lshl_b32 s8, s7, 12
	s_mov_b32 s7, s2
	s_add_u32 s6, s6, s8
	s_addc_u32 s7, s7, 0
	s_add_u32 s4, s4, 0x5200000
	s_addc_u32 s5, s5, 0
	v_readlane_b32 s8, v252, 25
	v_readlane_b32 s9, v252, 26
	s_nop 3
	v_lshlrev_b32_e32 v120, 4, v0
	v_lshlrev_b32_e32 v121, 3, v0
	v_lshlrev_b32_e32 v122, 2, v214
	v_lshlrev_b32_e32 v123, 2, v215
	v_lshlrev_b32_e32 v124, 2, v216
	v_lshlrev_b32_e32 v125, 2, v217
	v_lshlrev_b32_e32 v126, 2, v218
	v_lshlrev_b32_e32 v127, 2, v219
	s_lshl_b32 s2, s100, 17
	s_add_u32 s8, s8, s2
	s_addc_u32 s9, s9, 0
	s_lshl_b32 s2, s100, 16
	s_add_u32 s4, s4, s2
	s_addc_u32 s5, s5, 0
	global_load_dwordx4 v[0:3], v120, s[6:7] offset:0
	global_load_dwordx4 v[4:7], v120, s[6:7] offset:1024
	global_load_dwordx4 v[8:11], v120, s[6:7] offset:2048
	global_load_dwordx4 v[12:15], v120, s[6:7] offset:3072
	v_readlane_b32 s6, v252, 32
	v_readlane_b32 s7, v252, 33
	s_lshr_b32 s2, s100, 6
	s_mul_i32 s2, s2, 0x6000
	s_nop 3
	s_add_u32 s6, s6, s2
	s_addc_u32 s7, s7, 0
	s_add_u32 s6, s6, 0x1000
	s_addc_u32 s7, s7, 0
	global_load_dwordx4 v[16:19], v120, s[6:7] offset:0
	global_load_dwordx4 v[20:23], v120, s[6:7] offset:1024
	global_load_dwordx4 v[24:27], v120, s[6:7] offset:2048
	global_load_dwordx4 v[28:31], v120, s[6:7] offset:3072
	s_sub_u32 s6, s6, 0x1000
	s_subb_u32 s7, s7, 0
	global_load_dwordx4 v[32:35], v120, s[6:7] offset:0
	global_load_dwordx4 v[36:39], v120, s[6:7] offset:1024
	global_load_dwordx4 v[40:43], v120, s[6:7] offset:2048
	global_load_dwordx4 v[44:47], v120, s[6:7] offset:3072
	s_waitcnt vmcnt(0)
	v_add_f32_e32 v16, 1.0, v16
	v_add_f32_e32 v17, 1.0, v17
	v_add_f32_e32 v18, 1.0, v18
	v_add_f32_e32 v19, 1.0, v19
	v_add_f32_e32 v20, 1.0, v20
	v_add_f32_e32 v21, 1.0, v21
	v_add_f32_e32 v22, 1.0, v22
	v_add_f32_e32 v23, 1.0, v23
	v_add_f32_e32 v24, 1.0, v24
	v_add_f32_e32 v25, 1.0, v25
	v_add_f32_e32 v26, 1.0, v26
	v_add_f32_e32 v27, 1.0, v27
	v_add_f32_e32 v28, 1.0, v28
	v_add_f32_e32 v29, 1.0, v29
	v_add_f32_e32 v30, 1.0, v30
	v_add_f32_e32 v31, 1.0, v31
	s_movk_i32 s2, 8
.Lrms_sub0_loop:
	global_load_dwordx4 v[48:51], v120, s[8:9] offset:0
	global_load_dwordx4 v[52:55], v120, s[8:9] offset:1024
	global_load_dwordx4 v[56:59], v120, s[8:9] offset:2048
	global_load_dwordx4 v[60:63], v120, s[8:9] offset:3072
	s_add_u32 s8, s8, 0x1000
	s_addc_u32 s9, s9, 0
	global_load_dwordx4 v[64:67], v120, s[8:9] offset:0
	global_load_dwordx4 v[68:71], v120, s[8:9] offset:1024
	global_load_dwordx4 v[72:75], v120, s[8:9] offset:2048
	global_load_dwordx4 v[76:79], v120, s[8:9] offset:3072
	s_add_u32 s8, s8, 0x1000
	s_addc_u32 s9, s9, 0
	global_load_dwordx4 v[80:83], v120, s[8:9] offset:0
	global_load_dwordx4 v[84:87], v120, s[8:9] offset:1024
	global_load_dwordx4 v[88:91], v120, s[8:9] offset:2048
	global_load_dwordx4 v[92:95], v120, s[8:9] offset:3072
	s_add_u32 s8, s8, 0x1000
	s_addc_u32 s9, s9, 0
	global_load_dwordx4 v[96:99], v120, s[8:9] offset:0
	global_load_dwordx4 v[100:103], v120, s[8:9] offset:1024
	global_load_dwordx4 v[104:107], v120, s[8:9] offset:2048
	global_load_dwordx4 v[108:111], v120, s[8:9] offset:3072
	s_add_u32 s8, s8, 0x1000
	s_addc_u32 s9, s9, 0
	s_waitcnt vmcnt(12)
	v_mul_f32_e32 v112, v48, v48
	v_fmac_f32_e32 v112, v49, v49
	v_fmac_f32_e32 v112, v50, v50
	v_fmac_f32_e32 v112, v51, v51
	v_fmac_f32_e32 v112, v52, v52
	v_fmac_f32_e32 v112, v53, v53
	v_fmac_f32_e32 v112, v54, v54
	v_fmac_f32_e32 v112, v55, v55
	v_fmac_f32_e32 v112, v56, v56
	v_fmac_f32_e32 v112, v57, v57
	v_fmac_f32_e32 v112, v58, v58
	v_fmac_f32_e32 v112, v59, v59
	v_fmac_f32_e32 v112, v60, v60
	v_fmac_f32_e32 v112, v61, v61
	v_fmac_f32_e32 v112, v62, v62
	v_fmac_f32_e32 v112, v63, v63
	s_waitcnt vmcnt(8)
	v_mul_f32_e32 v113, v64, v64
	v_fmac_f32_e32 v113, v65, v65
	v_fmac_f32_e32 v113, v66, v66
	v_fmac_f32_e32 v113, v67, v67
	v_fmac_f32_e32 v113, v68, v68
	v_fmac_f32_e32 v113, v69, v69
	v_fmac_f32_e32 v113, v70, v70
	v_fmac_f32_e32 v113, v71, v71
	v_fmac_f32_e32 v113, v72, v72
	v_fmac_f32_e32 v113, v73, v73
	v_fmac_f32_e32 v113, v74, v74
	v_fmac_f32_e32 v113, v75, v75
	v_fmac_f32_e32 v113, v76, v76
	v_fmac_f32_e32 v113, v77, v77
	v_fmac_f32_e32 v113, v78, v78
	v_fmac_f32_e32 v113, v79, v79
	s_waitcnt vmcnt(4)
	v_mul_f32_e32 v114, v80, v80
	v_fmac_f32_e32 v114, v81, v81
	v_fmac_f32_e32 v114, v82, v82
	v_fmac_f32_e32 v114, v83, v83
	v_fmac_f32_e32 v114, v84, v84
	v_fmac_f32_e32 v114, v85, v85
	v_fmac_f32_e32 v114, v86, v86
	v_fmac_f32_e32 v114, v87, v87
	v_fmac_f32_e32 v114, v88, v88
	v_fmac_f32_e32 v114, v89, v89
	v_fmac_f32_e32 v114, v90, v90
	v_fmac_f32_e32 v114, v91, v91
	v_fmac_f32_e32 v114, v92, v92
	v_fmac_f32_e32 v114, v93, v93
	v_fmac_f32_e32 v114, v94, v94
	v_fmac_f32_e32 v114, v95, v95
	s_waitcnt vmcnt(0)
	v_mul_f32_e32 v115, v96, v96
	v_fmac_f32_e32 v115, v97, v97
	v_fmac_f32_e32 v115, v98, v98
	v_fmac_f32_e32 v115, v99, v99
	v_fmac_f32_e32 v115, v100, v100
	v_fmac_f32_e32 v115, v101, v101
	v_fmac_f32_e32 v115, v102, v102
	v_fmac_f32_e32 v115, v103, v103
	v_fmac_f32_e32 v115, v104, v104
	v_fmac_f32_e32 v115, v105, v105
	v_fmac_f32_e32 v115, v106, v106
	v_fmac_f32_e32 v115, v107, v107
	v_fmac_f32_e32 v115, v108, v108
	v_fmac_f32_e32 v115, v109, v109
	v_fmac_f32_e32 v115, v110, v110
	v_fmac_f32_e32 v115, v111, v111
	ds_bpermute_b32 v116, v122, v112
	ds_bpermute_b32 v117, v122, v113
	ds_bpermute_b32 v118, v122, v114
	ds_bpermute_b32 v119, v122, v115
	s_waitcnt lgkmcnt(0)
	v_add_f32_e32 v112, v112, v116
	v_add_f32_e32 v113, v113, v117
	v_add_f32_e32 v114, v114, v118
	v_add_f32_e32 v115, v115, v119
	ds_bpermute_b32 v116, v123, v112
	ds_bpermute_b32 v117, v123, v113
	ds_bpermute_b32 v118, v123, v114
	ds_bpermute_b32 v119, v123, v115
	s_waitcnt lgkmcnt(0)
	v_add_f32_e32 v112, v112, v116
	v_add_f32_e32 v113, v113, v117
	v_add_f32_e32 v114, v114, v118
	v_add_f32_e32 v115, v115, v119
	ds_bpermute_b32 v116, v124, v112
	ds_bpermute_b32 v117, v124, v113
	ds_bpermute_b32 v118, v124, v114
	ds_bpermute_b32 v119, v124, v115
	s_waitcnt lgkmcnt(0)
	v_add_f32_e32 v112, v112, v116
	v_add_f32_e32 v113, v113, v117
	v_add_f32_e32 v114, v114, v118
	v_add_f32_e32 v115, v115, v119
	ds_bpermute_b32 v116, v125, v112
	ds_bpermute_b32 v117, v125, v113
	ds_bpermute_b32 v118, v125, v114
	ds_bpermute_b32 v119, v125, v115
	s_waitcnt lgkmcnt(0)
	v_add_f32_e32 v112, v112, v116
	v_add_f32_e32 v113, v113, v117
	v_add_f32_e32 v114, v114, v118
	v_add_f32_e32 v115, v115, v119
	ds_bpermute_b32 v116, v126, v112
	ds_bpermute_b32 v117, v126, v113
	ds_bpermute_b32 v118, v126, v114
	ds_bpermute_b32 v119, v126, v115
	s_waitcnt lgkmcnt(0)
	v_add_f32_e32 v112, v112, v116
	v_add_f32_e32 v113, v113, v117
	v_add_f32_e32 v114, v114, v118
	v_add_f32_e32 v115, v115, v119
	ds_bpermute_b32 v116, v127, v112
	ds_bpermute_b32 v117, v127, v113
	ds_bpermute_b32 v118, v127, v114
	ds_bpermute_b32 v119, v127, v115
	s_waitcnt lgkmcnt(0)
	v_add_f32_e32 v112, v112, v116
	v_add_f32_e32 v113, v113, v117
	v_add_f32_e32 v114, v114, v118
	v_add_f32_e32 v115, v115, v119
	v_fmamk_f32 v112, v112, 0x3a800000, v208
	v_fmamk_f32 v113, v113, 0x3a800000, v208
	v_fmamk_f32 v114, v114, 0x3a800000, v208
	v_fmamk_f32 v115, v115, 0x3a800000, v208
	v_rsq_f32_e32 v112, v112
	v_rsq_f32_e32 v113, v113
	v_rsq_f32_e32 v114, v114
	v_rsq_f32_e32 v115, v115
	s_nop 1
	v_mul_f32_e32 v48, v48, v112
	v_mul_f32_e32 v49, v49, v112
	v_mul_f32_e32 v50, v50, v112
	v_mul_f32_e32 v51, v51, v112
	v_mul_f32_e32 v48, v0, v48
	v_mul_f32_e32 v49, v1, v49
	v_mul_f32_e32 v50, v2, v50
	v_mul_f32_e32 v51, v3, v51
	v_fma_f32 v48, v48, v16, v32
	v_fma_f32 v49, v49, v17, v33
	v_fma_f32 v50, v50, v18, v34
	v_fma_f32 v51, v51, v19, v35
	v_cvt_pk_bf16_f32 v128, v48, v49
	v_cvt_pk_bf16_f32 v129, v50, v51
	global_store_dwordx2 v121, v[128:129], s[4:5] offset:0
	v_mul_f32_e32 v52, v52, v112
	v_mul_f32_e32 v53, v53, v112
	v_mul_f32_e32 v54, v54, v112
	v_mul_f32_e32 v55, v55, v112
	v_mul_f32_e32 v52, v4, v52
	v_mul_f32_e32 v53, v5, v53
	v_mul_f32_e32 v54, v6, v54
	v_mul_f32_e32 v55, v7, v55
	v_fma_f32 v52, v52, v20, v36
	v_fma_f32 v53, v53, v21, v37
	v_fma_f32 v54, v54, v22, v38
	v_fma_f32 v55, v55, v23, v39
	v_cvt_pk_bf16_f32 v130, v52, v53
	v_cvt_pk_bf16_f32 v131, v54, v55
	global_store_dwordx2 v121, v[130:131], s[4:5] offset:512
	v_mul_f32_e32 v56, v56, v112
	v_mul_f32_e32 v57, v57, v112
	v_mul_f32_e32 v58, v58, v112
	v_mul_f32_e32 v59, v59, v112
	v_mul_f32_e32 v56, v8, v56
	v_mul_f32_e32 v57, v9, v57
	v_mul_f32_e32 v58, v10, v58
	v_mul_f32_e32 v59, v11, v59
	v_fma_f32 v56, v56, v24, v40
	v_fma_f32 v57, v57, v25, v41
	v_fma_f32 v58, v58, v26, v42
	v_fma_f32 v59, v59, v27, v43
	v_cvt_pk_bf16_f32 v128, v56, v57
	v_cvt_pk_bf16_f32 v129, v58, v59
	global_store_dwordx2 v121, v[128:129], s[4:5] offset:1024
	v_mul_f32_e32 v60, v60, v112
	v_mul_f32_e32 v61, v61, v112
	v_mul_f32_e32 v62, v62, v112
	v_mul_f32_e32 v63, v63, v112
	v_mul_f32_e32 v60, v12, v60
	v_mul_f32_e32 v61, v13, v61
	v_mul_f32_e32 v62, v14, v62
	v_mul_f32_e32 v63, v15, v63
	v_fma_f32 v60, v60, v28, v44
	v_fma_f32 v61, v61, v29, v45
	v_fma_f32 v62, v62, v30, v46
	v_fma_f32 v63, v63, v31, v47
	v_cvt_pk_bf16_f32 v130, v60, v61
	v_cvt_pk_bf16_f32 v131, v62, v63
	global_store_dwordx2 v121, v[130:131], s[4:5] offset:1536
	s_add_u32 s4, s4, 0x800
	s_addc_u32 s5, s5, 0
	v_mul_f32_e32 v64, v64, v113
	v_mul_f32_e32 v65, v65, v113
	v_mul_f32_e32 v66, v66, v113
	v_mul_f32_e32 v67, v67, v113
	v_mul_f32_e32 v64, v0, v64
	v_mul_f32_e32 v65, v1, v65
	v_mul_f32_e32 v66, v2, v66
	v_mul_f32_e32 v67, v3, v67
	v_fma_f32 v64, v64, v16, v32
	v_fma_f32 v65, v65, v17, v33
	v_fma_f32 v66, v66, v18, v34
	v_fma_f32 v67, v67, v19, v35
	v_cvt_pk_bf16_f32 v128, v64, v65
	v_cvt_pk_bf16_f32 v129, v66, v67
	global_store_dwordx2 v121, v[128:129], s[4:5] offset:0
	v_mul_f32_e32 v68, v68, v113
	v_mul_f32_e32 v69, v69, v113
	v_mul_f32_e32 v70, v70, v113
	v_mul_f32_e32 v71, v71, v113
	v_mul_f32_e32 v68, v4, v68
	v_mul_f32_e32 v69, v5, v69
	v_mul_f32_e32 v70, v6, v70
	v_mul_f32_e32 v71, v7, v71
	v_fma_f32 v68, v68, v20, v36
	v_fma_f32 v69, v69, v21, v37
	v_fma_f32 v70, v70, v22, v38
	v_fma_f32 v71, v71, v23, v39
	v_cvt_pk_bf16_f32 v130, v68, v69
	v_cvt_pk_bf16_f32 v131, v70, v71
	global_store_dwordx2 v121, v[130:131], s[4:5] offset:512
	v_mul_f32_e32 v72, v72, v113
	v_mul_f32_e32 v73, v73, v113
	v_mul_f32_e32 v74, v74, v113
	v_mul_f32_e32 v75, v75, v113
	v_mul_f32_e32 v72, v8, v72
	v_mul_f32_e32 v73, v9, v73
	v_mul_f32_e32 v74, v10, v74
	v_mul_f32_e32 v75, v11, v75
	v_fma_f32 v72, v72, v24, v40
	v_fma_f32 v73, v73, v25, v41
	v_fma_f32 v74, v74, v26, v42
	v_fma_f32 v75, v75, v27, v43
	v_cvt_pk_bf16_f32 v128, v72, v73
	v_cvt_pk_bf16_f32 v129, v74, v75
	global_store_dwordx2 v121, v[128:129], s[4:5] offset:1024
	v_mul_f32_e32 v76, v76, v113
	v_mul_f32_e32 v77, v77, v113
	v_mul_f32_e32 v78, v78, v113
	v_mul_f32_e32 v79, v79, v113
	v_mul_f32_e32 v76, v12, v76
	v_mul_f32_e32 v77, v13, v77
	v_mul_f32_e32 v78, v14, v78
	v_mul_f32_e32 v79, v15, v79
	v_fma_f32 v76, v76, v28, v44
	v_fma_f32 v77, v77, v29, v45
	v_fma_f32 v78, v78, v30, v46
	v_fma_f32 v79, v79, v31, v47
	v_cvt_pk_bf16_f32 v130, v76, v77
	v_cvt_pk_bf16_f32 v131, v78, v79
	global_store_dwordx2 v121, v[130:131], s[4:5] offset:1536
	s_add_u32 s4, s4, 0x800
	s_addc_u32 s5, s5, 0
	v_mul_f32_e32 v80, v80, v114
	v_mul_f32_e32 v81, v81, v114
	v_mul_f32_e32 v82, v82, v114
	v_mul_f32_e32 v83, v83, v114
	v_mul_f32_e32 v80, v0, v80
	v_mul_f32_e32 v81, v1, v81
	v_mul_f32_e32 v82, v2, v82
	v_mul_f32_e32 v83, v3, v83
	v_fma_f32 v80, v80, v16, v32
	v_fma_f32 v81, v81, v17, v33
	v_fma_f32 v82, v82, v18, v34
	v_fma_f32 v83, v83, v19, v35
	v_cvt_pk_bf16_f32 v128, v80, v81
	v_cvt_pk_bf16_f32 v129, v82, v83
	global_store_dwordx2 v121, v[128:129], s[4:5] offset:0
	v_mul_f32_e32 v84, v84, v114
	v_mul_f32_e32 v85, v85, v114
	v_mul_f32_e32 v86, v86, v114
	v_mul_f32_e32 v87, v87, v114
	v_mul_f32_e32 v84, v4, v84
	v_mul_f32_e32 v85, v5, v85
	v_mul_f32_e32 v86, v6, v86
	v_mul_f32_e32 v87, v7, v87
	v_fma_f32 v84, v84, v20, v36
	v_fma_f32 v85, v85, v21, v37
	v_fma_f32 v86, v86, v22, v38
	v_fma_f32 v87, v87, v23, v39
	v_cvt_pk_bf16_f32 v130, v84, v85
	v_cvt_pk_bf16_f32 v131, v86, v87
	global_store_dwordx2 v121, v[130:131], s[4:5] offset:512
	v_mul_f32_e32 v88, v88, v114
	v_mul_f32_e32 v89, v89, v114
	v_mul_f32_e32 v90, v90, v114
	v_mul_f32_e32 v91, v91, v114
	v_mul_f32_e32 v88, v8, v88
	v_mul_f32_e32 v89, v9, v89
	v_mul_f32_e32 v90, v10, v90
	v_mul_f32_e32 v91, v11, v91
	v_fma_f32 v88, v88, v24, v40
	v_fma_f32 v89, v89, v25, v41
	v_fma_f32 v90, v90, v26, v42
	v_fma_f32 v91, v91, v27, v43
	v_cvt_pk_bf16_f32 v128, v88, v89
	v_cvt_pk_bf16_f32 v129, v90, v91
	global_store_dwordx2 v121, v[128:129], s[4:5] offset:1024
	v_mul_f32_e32 v92, v92, v114
	v_mul_f32_e32 v93, v93, v114
	v_mul_f32_e32 v94, v94, v114
	v_mul_f32_e32 v95, v95, v114
	v_mul_f32_e32 v92, v12, v92
	v_mul_f32_e32 v93, v13, v93
	v_mul_f32_e32 v94, v14, v94
	v_mul_f32_e32 v95, v15, v95
	v_fma_f32 v92, v92, v28, v44
	v_fma_f32 v93, v93, v29, v45
	v_fma_f32 v94, v94, v30, v46
	v_fma_f32 v95, v95, v31, v47
	v_cvt_pk_bf16_f32 v130, v92, v93
	v_cvt_pk_bf16_f32 v131, v94, v95
	global_store_dwordx2 v121, v[130:131], s[4:5] offset:1536
	s_add_u32 s4, s4, 0x800
	s_addc_u32 s5, s5, 0
	v_mul_f32_e32 v96, v96, v115
	v_mul_f32_e32 v97, v97, v115
	v_mul_f32_e32 v98, v98, v115
	v_mul_f32_e32 v99, v99, v115
	v_mul_f32_e32 v96, v0, v96
	v_mul_f32_e32 v97, v1, v97
	v_mul_f32_e32 v98, v2, v98
	v_mul_f32_e32 v99, v3, v99
	v_fma_f32 v96, v96, v16, v32
	v_fma_f32 v97, v97, v17, v33
	v_fma_f32 v98, v98, v18, v34
	v_fma_f32 v99, v99, v19, v35
	v_cvt_pk_bf16_f32 v128, v96, v97
	v_cvt_pk_bf16_f32 v129, v98, v99
	global_store_dwordx2 v121, v[128:129], s[4:5] offset:0
	v_mul_f32_e32 v100, v100, v115
	v_mul_f32_e32 v101, v101, v115
	v_mul_f32_e32 v102, v102, v115
	v_mul_f32_e32 v103, v103, v115
	v_mul_f32_e32 v100, v4, v100
	v_mul_f32_e32 v101, v5, v101
	v_mul_f32_e32 v102, v6, v102
	v_mul_f32_e32 v103, v7, v103
	v_fma_f32 v100, v100, v20, v36
	v_fma_f32 v101, v101, v21, v37
	v_fma_f32 v102, v102, v22, v38
	v_fma_f32 v103, v103, v23, v39
	v_cvt_pk_bf16_f32 v130, v100, v101
	v_cvt_pk_bf16_f32 v131, v102, v103
	global_store_dwordx2 v121, v[130:131], s[4:5] offset:512
	v_mul_f32_e32 v104, v104, v115
	v_mul_f32_e32 v105, v105, v115
	v_mul_f32_e32 v106, v106, v115
	v_mul_f32_e32 v107, v107, v115
	v_mul_f32_e32 v104, v8, v104
	v_mul_f32_e32 v105, v9, v105
	v_mul_f32_e32 v106, v10, v106
	v_mul_f32_e32 v107, v11, v107
	v_fma_f32 v104, v104, v24, v40
	v_fma_f32 v105, v105, v25, v41
	v_fma_f32 v106, v106, v26, v42
	v_fma_f32 v107, v107, v27, v43
	v_cvt_pk_bf16_f32 v128, v104, v105
	v_cvt_pk_bf16_f32 v129, v106, v107
	global_store_dwordx2 v121, v[128:129], s[4:5] offset:1024
	v_mul_f32_e32 v108, v108, v115
	v_mul_f32_e32 v109, v109, v115
	v_mul_f32_e32 v110, v110, v115
	v_mul_f32_e32 v111, v111, v115
	v_mul_f32_e32 v108, v12, v108
	v_mul_f32_e32 v109, v13, v109
	v_mul_f32_e32 v110, v14, v110
	v_mul_f32_e32 v111, v15, v111
	v_fma_f32 v108, v108, v28, v44
	v_fma_f32 v109, v109, v29, v45
	v_fma_f32 v110, v110, v30, v46
	v_fma_f32 v111, v111, v31, v47
	v_cvt_pk_bf16_f32 v130, v108, v109
	v_cvt_pk_bf16_f32 v131, v110, v111
	global_store_dwordx2 v121, v[130:131], s[4:5] offset:1536
	s_add_u32 s4, s4, 0x800
	s_addc_u32 s5, s5, 0
	s_sub_u32 s2, s2, 1
	s_cmp_lg_u32 s2, 0
	s_cbranch_scc1 .Lrms_sub0_loop

	.amdhsa_kernel _Z8mega_fwdILi1023EEv2KP
		.amdhsa_group_segment_fixed_size 0
		.amdhsa_private_segment_fixed_size 0
		.amdhsa_kernarg_size 504
		.amdhsa_user_sgpr_count 2
		.amdhsa_user_sgpr_dispatch_ptr 0
		.amdhsa_user_sgpr_queue_ptr 0
		.amdhsa_user_sgpr_kernarg_segment_ptr 1
		.amdhsa_user_sgpr_dispatch_id 0
		.amdhsa_user_sgpr_kernarg_preload_length 0
		.amdhsa_user_sgpr_kernarg_preload_offset 0
		.amdhsa_user_sgpr_private_segment_size 0
		.amdhsa_uses_dynamic_stack 0
		.amdhsa_enable_private_segment 0
		.amdhsa_system_sgpr_workgroup_id_x 1
		.amdhsa_system_sgpr_workgroup_id_y 0
		.amdhsa_system_sgpr_workgroup_id_z 0
		.amdhsa_system_sgpr_workgroup_info 0
		.amdhsa_system_vgpr_workitem_id 2
		.amdhsa_next_free_vgpr 255
		.amdhsa_next_free_sgpr 102
		.amdhsa_accum_offset 256
		.amdhsa_reserve_vcc 1
		.amdhsa_float_round_mode_32 0
		.amdhsa_float_round_mode_16_64 0
		.amdhsa_float_denorm_mode_32 3
		.amdhsa_float_denorm_mode_16_64 3
		.amdhsa_dx10_clamp 1
		.amdhsa_ieee_mode 1
		.amdhsa_fp16_overflow 0
		.amdhsa_tg_split 0
		.amdhsa_exception_fp_ieee_invalid_op 0
		.amdhsa_exception_fp_denorm_src 0
		.amdhsa_exception_fp_ieee_div_zero 0
		.amdhsa_exception_fp_ieee_overflow 0
		.amdhsa_exception_fp_ieee_underflow 0
		.amdhsa_exception_fp_ieee_inexact 0
		.amdhsa_exception_int_div_zero 0
	.end_amdhsa_kernel

amdhsa.kernels:
  - .agpr_count:     0
    .args:
      - .offset:         0
        .size:           248
        .value_kind:     by_value
      - .offset:         248
        .size:           4
        .value_kind:     hidden_block_count_x
      - .offset:         252
        .size:           4
        .value_kind:     hidden_block_count_y
      - .offset:         256
        .size:           4
        .value_kind:     hidden_block_count_z
      - .offset:         260
        .size:           2
        .value_kind:     hidden_group_size_x
      - .offset:         262
        .size:           2
        .value_kind:     hidden_group_size_y
      - .offset:         264
        .size:           2
        .value_kind:     hidden_group_size_z
      - .offset:         266
        .size:           2
        .value_kind:     hidden_remainder_x
      - .offset:         268
        .size:           2
        .value_kind:     hidden_remainder_y
      - .offset:         270
        .size:           2
        .value_kind:     hidden_remainder_z
      - .offset:         288
        .size:           8
        .value_kind:     hidden_global_offset_x
      - .offset:         296
        .size:           8
        .value_kind:     hidden_global_offset_y
      - .offset:         304
        .size:           8
        .value_kind:     hidden_global_offset_z
      - .offset:         312
        .size:           2
        .value_kind:     hidden_grid_dims
      - .offset:         336
        .size:           8
        .value_kind:     hidden_multigrid_sync_arg
      - .offset:         368
        .size:           4
        .value_kind:     hidden_dynamic_lds_size
    .group_segment_fixed_size: 0
    .kernarg_segment_align: 8
    .kernarg_segment_size: 504
    .language:       OpenCL C
    .language_version:
      - 2
      - 0
    .max_flat_workgroup_size: 512
    .name:           _Z8mega_fwdILi1023EEv2KP
    .private_segment_fixed_size: 0
    .sgpr_count:     108
    .sgpr_spill_count: 176
    .symbol:         _Z8mega_fwdILi1023EEv2KP.kd
    .uniform_work_group_size: 1
    .uses_dynamic_stack: false
    .vgpr_count:     255
    .vgpr_spill_count: 0
    .wavefront_size: 64
